# v80 plus hand-written 256x128 16x16x32 tiles on the 256-workgroup path of MLP2A/MLP2B (the earlier n128 hand tiles sat on the generic-grid path that a 256-workgroup launch never takes): 16-byte residu
# speedup vs baseline: 1.0516x; 1.0155x over previous
.LBB0_68:
	s_andn2_b64 vcc, exec, s[26:27]
	s_mov_b64 s[26:27], 0
	s_cbranch_vccnz .LBB0_107
	v_readlane_b32 s24, v236, 3
	v_readlane_b32 s25, v236, 4
	s_andn2_b64 vcc, exec, s[24:25]
	s_cbranch_vccnz .LBB0_88
	s_add_u32 s26, s46, 0xaa08000
	s_addc_u32 s27, s47, 0
	v_readlane_b32 s24, v236, 5
	v_readlane_b32 s25, v236, 9
	s_branch .LBB0_72
.LBB0_72:
	s_and_b32 s28, s25, 56
	s_or_b32 s29, s28, s83
	s_lshl_b32 s35, s29, 8
	s_cmp_gt_u32 s28, 39
	s_mov_b64 s[28:29], -1
	s_cbranch_scc0 .LBB0_74
	s_add_i32 s90, s35, 0xffffd800
	s_mov_b64 s[28:29], 0

.LBB0_76:
	s_waitcnt lgkmcnt(0)
	s_lshl_b64 s[36:37], s[90:91], 13
	s_add_u32 s36, s36, s28
	s_addc_u32 s37, s37, s29
	s_and_b32 s30, s25, 7
	s_lshl_b32 s30, s30, 7
	s_lshl_b32 s69, s30, 13
	s_add_u32 s52, s50, s69
	s_addc_u32 s53, s51, 0
	v_readfirstlane_b32 s69, v200
	s_lshr_b32 s69, s69, 6
	s_lshl_b32 s31, s69, 11
	s_add_u32 s31, s31, 16
	s_lshl_b32 s32, s69, 10
	s_add_u32 s32, s32, 0x4010
	s_lshl_b32 s69, s69, 17
	s_add_u32 s52, s52, s69
	s_addc_u32 s53, s53, 0
	s_lshl_b32 s69, s69, 1
	s_add_u32 s36, s36, s69
	s_addc_u32 s37, s37, 0
	v_bfe_u32 v173, v200, 4, 2
	v_sub_u32_e32 v173, 0, v173
	v_and_b32_e32 v173, 3, v173
	v_and_b32_e32 v172, 3, v200
	v_xor_b32_e32 v172, v172, v173
	v_bfe_u32 v173, v200, 2, 4
	v_lshlrev_b32_e32 v173, 13, v173
	v_lshl_or_b32 v170, v172, 4, v173
	v_add_u32_e32 v171, 0x20000, v170
	v_bfe_u32 v172, v200, 2, 2
	v_sub_u32_e32 v172, 0, v172
	v_and_b32_e32 v172, 3, v172
	v_bfe_u32 v173, v200, 4, 2
	v_xor_b32_e32 v172, v172, v173
	v_and_b32_e32 v173, 15, v200
	v_bfe_u32 v174, v200, 7, 2
	v_lshl_or_b32 v174, v174, 6, v173
	v_lshlrev_b32_e32 v174, 6, v174
	v_lshl_or_b32 v164, v172, 4, v174
	v_bfe_u32 v174, v200, 6, 1
	v_lshl_or_b32 v174, v174, 6, v173
	v_lshlrev_b32_e32 v174, 6, v174
	v_lshl_or_b32 v165, v172, 4, v174
	v_add_u32_e32 v165, 0x4000, v165
	v_bfe_u32 v172, v200, 6, 1
	v_bfe_u32 v173, v200, 4, 2
	v_lshlrev_b32_e32 v172, 6, v172
	v_lshl_or_b32 v172, v173, 2, v172
	v_add_u32_e32 v172, s30, v172
	v_lshlrev_b32_e32 v172, 2, v172
	global_load_dwordx4 v[132:135], v172, s[44:45]
	global_load_dwordx4 v[136:139], v172, s[44:45] offset:64
	global_load_dwordx4 v[140:143], v172, s[44:45] offset:128
	global_load_dwordx4 v[144:147], v172, s[44:45] offset:192
	s_mov_b32 s65, 0x0
	s_add_u32 m0, s31, s65
	s_nop 0
	global_load_lds_dwordx4 v170, s[36:37]
	s_add_u32 m0, s31, s65
	s_add_u32 m0, m0, 0x400
	s_nop 0
	global_load_lds_dwordx4 v171, s[36:37]
	s_add_u32 m0, s32, s65
	s_nop 0
	global_load_lds_dwordx4 v170, s[52:53]
	s_add_u32 s36, s36, 64
	s_addc_u32 s37, s37, 0
	s_add_u32 s52, s52, 64
	s_addc_u32 s53, s53, 0
	s_mov_b32 s65, 0x6000
	s_add_u32 m0, s31, s65
	s_nop 0
	global_load_lds_dwordx4 v170, s[36:37]
	s_add_u32 m0, s31, s65
	s_add_u32 m0, m0, 0x400
	s_nop 0
	global_load_lds_dwordx4 v171, s[36:37]
	s_add_u32 m0, s32, s65
	s_nop 0
	global_load_lds_dwordx4 v170, s[52:53]
	s_add_u32 s36, s36, 64
	s_addc_u32 s37, s37, 0
	s_add_u32 s52, s52, 64
	s_addc_u32 s53, s53, 0
	s_mov_b32 s65, 0xc000
	s_add_u32 m0, s31, s65
	s_nop 0
	global_load_lds_dwordx4 v170, s[36:37]
	s_add_u32 m0, s31, s65
	s_add_u32 m0, m0, 0x400
	s_nop 0
	global_load_lds_dwordx4 v171, s[36:37]
	s_add_u32 m0, s32, s65
	s_nop 0
	global_load_lds_dwordx4 v170, s[52:53]
	s_add_u32 s36, s36, 64
	s_addc_u32 s37, s37, 0
	s_add_u32 s52, s52, 64
	s_addc_u32 s53, s53, 0
	s_mov_b32 s65, 0x12000
	s_add_u32 m0, s31, s65
	s_nop 0
	global_load_lds_dwordx4 v170, s[36:37]
	s_add_u32 m0, s31, s65
	s_add_u32 m0, m0, 0x400
	s_nop 0
	global_load_lds_dwordx4 v171, s[36:37]
	s_add_u32 m0, s32, s65
	s_nop 0
	global_load_lds_dwordx4 v170, s[52:53]
	s_add_u32 s36, s36, 64
	s_addc_u32 s37, s37, 0
	s_add_u32 s52, s52, 64
	s_addc_u32 s53, s53, 0
	s_waitcnt vmcnt(12)
	v_mov_b32_e32 v4, v132
	v_mov_b32_e32 v5, v133
	v_mov_b32_e32 v6, v134
	v_mov_b32_e32 v7, v135
	v_mov_b32_e32 v8, v136
	v_mov_b32_e32 v9, v137
	v_mov_b32_e32 v10, v138
	v_mov_b32_e32 v11, v139
	v_mov_b32_e32 v12, v140
	v_mov_b32_e32 v13, v141
	v_mov_b32_e32 v14, v142
	v_mov_b32_e32 v15, v143
	v_mov_b32_e32 v16, v144
	v_mov_b32_e32 v17, v145
	v_mov_b32_e32 v18, v146
	v_mov_b32_e32 v19, v147
	v_mov_b32_e32 v20, v132
	v_mov_b32_e32 v21, v133
	v_mov_b32_e32 v22, v134
	v_mov_b32_e32 v23, v135
	v_mov_b32_e32 v24, v136
	v_mov_b32_e32 v25, v137
	v_mov_b32_e32 v26, v138
	v_mov_b32_e32 v27, v139
	v_mov_b32_e32 v28, v140
	v_mov_b32_e32 v29, v141
	v_mov_b32_e32 v30, v142
	v_mov_b32_e32 v31, v143
	v_mov_b32_e32 v32, v144
	v_mov_b32_e32 v33, v145
	v_mov_b32_e32 v34, v146
	v_mov_b32_e32 v35, v147
	v_mov_b32_e32 v36, v132
	v_mov_b32_e32 v37, v133
	v_mov_b32_e32 v38, v134
	v_mov_b32_e32 v39, v135
	v_mov_b32_e32 v40, v136
	v_mov_b32_e32 v41, v137
	v_mov_b32_e32 v42, v138
	v_mov_b32_e32 v43, v139
	v_mov_b32_e32 v44, v140
	v_mov_b32_e32 v45, v141
	v_mov_b32_e32 v46, v142
	v_mov_b32_e32 v47, v143
	v_mov_b32_e32 v48, v144
	v_mov_b32_e32 v49, v145
	v_mov_b32_e32 v50, v146
	v_mov_b32_e32 v51, v147
	v_mov_b32_e32 v52, v132
	v_mov_b32_e32 v53, v133
	v_mov_b32_e32 v54, v134
	v_mov_b32_e32 v55, v135
	v_mov_b32_e32 v56, v136
	v_mov_b32_e32 v57, v137
	v_mov_b32_e32 v58, v138
	v_mov_b32_e32 v59, v139
	v_mov_b32_e32 v60, v140
	v_mov_b32_e32 v61, v141
	v_mov_b32_e32 v62, v142
	v_mov_b32_e32 v63, v143
	v_mov_b32_e32 v64, v144
	v_mov_b32_e32 v65, v145
	v_mov_b32_e32 v66, v146
	v_mov_b32_e32 v67, v147
	s_waitcnt vmcnt(9)
	s_barrier
	s_mov_b32 s34, 0
	s_mov_b32 s68, 0
	s_nop 1
	v_add_u32_e32 v168, s34, v165
	v_add_u32_e32 v169, s34, v164
	ds_read_b128 v[132:135], v168 offset:16
	ds_read_b128 v[136:139], v168 offset:1040
	ds_read_b128 v[140:143], v168 offset:2064
	ds_read_b128 v[144:147], v168 offset:3088
	ds_read_b128 v[184:187], v169 offset:16
	ds_read_b128 v[188:191], v169 offset:1040
	s_waitcnt lgkmcnt(0)
.Lt_mlp2bv:
	v_add_u32_e32 v169, s34, v164
	v_mfma_f32_16x16x32_f16 v[4:7], v[132:135], v[184:187], v[4:7]
	ds_read_b128 v[192:195], v169 offset:2064
	v_mfma_f32_16x16x32_f16 v[8:11], v[136:139], v[184:187], v[8:11]
	ds_read_b128 v[196:199], v169 offset:3088
	v_mfma_f32_16x16x32_f16 v[12:15], v[140:143], v[184:187], v[12:15]
	v_mfma_f32_16x16x32_f16 v[16:19], v[144:147], v[184:187], v[16:19]
	v_mfma_f32_16x16x32_f16 v[20:23], v[132:135], v[188:191], v[20:23]
	v_mfma_f32_16x16x32_f16 v[24:27], v[136:139], v[188:191], v[24:27]
	v_mfma_f32_16x16x32_f16 v[28:31], v[140:143], v[188:191], v[28:31]
	v_mfma_f32_16x16x32_f16 v[32:35], v[144:147], v[188:191], v[32:35]
	s_waitcnt vmcnt(6) lgkmcnt(0)
	s_barrier
	s_add_i32 s65, s34, 0x6000
	s_cmp_lg_u32 s34, 0x12000
	s_cselect_b32 s65, s65, 0
	v_add_u32_e32 v168, s65, v165
	v_add_u32_e32 v169, s65, v164
	v_mfma_f32_16x16x32_f16 v[36:39], v[132:135], v[192:195], v[36:39]
	ds_read_b128 v[148:151], v168 offset:16
	ds_read_b128 v[184:187], v169 offset:16
	v_mfma_f32_16x16x32_f16 v[40:43], v[136:139], v[192:195], v[40:43]
	ds_read_b128 v[152:155], v168 offset:1040
	ds_read_b128 v[188:191], v169 offset:1040
	v_mfma_f32_16x16x32_f16 v[44:47], v[140:143], v[192:195], v[44:47]
	ds_read_b128 v[156:159], v168 offset:2064
	v_mfma_f32_16x16x32_f16 v[48:51], v[144:147], v[192:195], v[48:51]
	ds_read_b128 v[160:163], v168 offset:3088
	v_mfma_f32_16x16x32_f16 v[52:55], v[132:135], v[196:199], v[52:55]
	s_add_u32 m0, s31, s34
	s_nop 0
	global_load_lds_dwordx4 v170, s[36:37]
	v_mfma_f32_16x16x32_f16 v[56:59], v[136:139], v[196:199], v[56:59]
	s_add_u32 m0, s31, s34
	s_add_u32 m0, m0, 0x400
	s_nop 0
	global_load_lds_dwordx4 v171, s[36:37]
	v_mfma_f32_16x16x32_f16 v[60:63], v[140:143], v[196:199], v[60:63]
	s_add_u32 m0, s32, s34
	s_nop 0
	global_load_lds_dwordx4 v170, s[52:53]
	v_mfma_f32_16x16x32_f16 v[64:67], v[144:147], v[196:199], v[64:67]
	s_waitcnt lgkmcnt(0)
	s_mov_b32 s34, s65
	s_add_u32 s36, s36, 64
	s_addc_u32 s37, s37, 0
	s_add_u32 s52, s52, 64
	s_addc_u32 s53, s53, 0
	v_add_u32_e32 v169, s34, v164
	v_mfma_f32_16x16x32_f16 v[4:7], v[148:151], v[184:187], v[4:7]
	ds_read_b128 v[192:195], v169 offset:2064
	v_mfma_f32_16x16x32_f16 v[8:11], v[152:155], v[184:187], v[8:11]
	ds_read_b128 v[196:199], v169 offset:3088
	v_mfma_f32_16x16x32_f16 v[12:15], v[156:159], v[184:187], v[12:15]
	v_mfma_f32_16x16x32_f16 v[16:19], v[160:163], v[184:187], v[16:19]
	v_mfma_f32_16x16x32_f16 v[20:23], v[148:151], v[188:191], v[20:23]
	v_mfma_f32_16x16x32_f16 v[24:27], v[152:155], v[188:191], v[24:27]
	v_mfma_f32_16x16x32_f16 v[28:31], v[156:159], v[188:191], v[28:31]
	v_mfma_f32_16x16x32_f16 v[32:35], v[160:163], v[188:191], v[32:35]
	s_waitcnt vmcnt(6) lgkmcnt(0)
	s_barrier
	s_add_i32 s65, s34, 0x6000
	s_cmp_lg_u32 s34, 0x12000
	s_cselect_b32 s65, s65, 0
	v_add_u32_e32 v168, s65, v165
	v_add_u32_e32 v169, s65, v164
	v_mfma_f32_16x16x32_f16 v[36:39], v[148:151], v[192:195], v[36:39]
	ds_read_b128 v[132:135], v168 offset:16
	ds_read_b128 v[184:187], v169 offset:16
	v_mfma_f32_16x16x32_f16 v[40:43], v[152:155], v[192:195], v[40:43]
	ds_read_b128 v[136:139], v168 offset:1040
	ds_read_b128 v[188:191], v169 offset:1040
	v_mfma_f32_16x16x32_f16 v[44:47], v[156:159], v[192:195], v[44:47]
	ds_read_b128 v[140:143], v168 offset:2064
	v_mfma_f32_16x16x32_f16 v[48:51], v[160:163], v[192:195], v[48:51]
	ds_read_b128 v[144:147], v168 offset:3088
	v_mfma_f32_16x16x32_f16 v[52:55], v[148:151], v[196:199], v[52:55]
	s_add_u32 m0, s31, s34
	s_nop 0
	global_load_lds_dwordx4 v170, s[36:37]
	v_mfma_f32_16x16x32_f16 v[56:59], v[152:155], v[196:199], v[56:59]
	s_add_u32 m0, s31, s34
	s_add_u32 m0, m0, 0x400
	s_nop 0
	global_load_lds_dwordx4 v171, s[36:37]
	v_mfma_f32_16x16x32_f16 v[60:63], v[156:159], v[196:199], v[60:63]
	s_add_u32 m0, s32, s34
	s_nop 0
	global_load_lds_dwordx4 v170, s[52:53]
	v_mfma_f32_16x16x32_f16 v[64:67], v[160:163], v[196:199], v[64:67]
	s_waitcnt lgkmcnt(0)
	s_mov_b32 s34, s65
	s_add_u32 s36, s36, 64
	s_addc_u32 s37, s37, 0
	s_add_u32 s52, s52, 64
	s_addc_u32 s53, s53, 0
	s_add_i32 s68, s68, 2
	s_cmp_lt_u32 s68, 124
	s_cbranch_scc1 .Lt_mlp2bv
	v_add_u32_e32 v169, s34, v164
	v_mfma_f32_16x16x32_f16 v[4:7], v[132:135], v[184:187], v[4:7]
	ds_read_b128 v[192:195], v169 offset:2064
	v_mfma_f32_16x16x32_f16 v[8:11], v[136:139], v[184:187], v[8:11]
	ds_read_b128 v[196:199], v169 offset:3088
	v_mfma_f32_16x16x32_f16 v[12:15], v[140:143], v[184:187], v[12:15]
	v_mfma_f32_16x16x32_f16 v[16:19], v[144:147], v[184:187], v[16:19]
	v_mfma_f32_16x16x32_f16 v[20:23], v[132:135], v[188:191], v[20:23]
	v_mfma_f32_16x16x32_f16 v[24:27], v[136:139], v[188:191], v[24:27]
	v_mfma_f32_16x16x32_f16 v[28:31], v[140:143], v[188:191], v[28:31]
	v_mfma_f32_16x16x32_f16 v[32:35], v[144:147], v[188:191], v[32:35]
	s_waitcnt vmcnt(6) lgkmcnt(0)
	s_barrier
	s_add_i32 s65, s34, 0x6000
	s_cmp_lg_u32 s34, 0x12000
	s_cselect_b32 s65, s65, 0
	v_add_u32_e32 v168, s65, v165
	v_add_u32_e32 v169, s65, v164
	v_mfma_f32_16x16x32_f16 v[36:39], v[132:135], v[192:195], v[36:39]
	ds_read_b128 v[148:151], v168 offset:16
	ds_read_b128 v[184:187], v169 offset:16
	v_mfma_f32_16x16x32_f16 v[40:43], v[136:139], v[192:195], v[40:43]
	ds_read_b128 v[152:155], v168 offset:1040
	ds_read_b128 v[188:191], v169 offset:1040
	v_mfma_f32_16x16x32_f16 v[44:47], v[140:143], v[192:195], v[44:47]
	ds_read_b128 v[156:159], v168 offset:2064
	v_mfma_f32_16x16x32_f16 v[48:51], v[144:147], v[192:195], v[48:51]
	ds_read_b128 v[160:163], v168 offset:3088
	v_mfma_f32_16x16x32_f16 v[52:55], v[132:135], v[196:199], v[52:55]
	v_mfma_f32_16x16x32_f16 v[56:59], v[136:139], v[196:199], v[56:59]
	v_mfma_f32_16x16x32_f16 v[60:63], v[140:143], v[196:199], v[60:63]
	v_mfma_f32_16x16x32_f16 v[64:67], v[144:147], v[196:199], v[64:67]
	s_waitcnt lgkmcnt(0)
	s_mov_b32 s34, s65
	v_add_u32_e32 v169, s34, v164
	v_mfma_f32_16x16x32_f16 v[4:7], v[148:151], v[184:187], v[4:7]
	ds_read_b128 v[192:195], v169 offset:2064
	v_mfma_f32_16x16x32_f16 v[8:11], v[152:155], v[184:187], v[8:11]
	ds_read_b128 v[196:199], v169 offset:3088
	v_mfma_f32_16x16x32_f16 v[12:15], v[156:159], v[184:187], v[12:15]
	v_mfma_f32_16x16x32_f16 v[16:19], v[160:163], v[184:187], v[16:19]
	v_mfma_f32_16x16x32_f16 v[20:23], v[148:151], v[188:191], v[20:23]
	v_mfma_f32_16x16x32_f16 v[24:27], v[152:155], v[188:191], v[24:27]
	v_mfma_f32_16x16x32_f16 v[28:31], v[156:159], v[188:191], v[28:31]
	v_mfma_f32_16x16x32_f16 v[32:35], v[160:163], v[188:191], v[32:35]
	s_waitcnt vmcnt(3) lgkmcnt(0)
	s_barrier
	s_add_i32 s65, s34, 0x6000
	s_cmp_lg_u32 s34, 0x12000
	s_cselect_b32 s65, s65, 0
	v_add_u32_e32 v168, s65, v165
	v_add_u32_e32 v169, s65, v164
	v_mfma_f32_16x16x32_f16 v[36:39], v[148:151], v[192:195], v[36:39]
	ds_read_b128 v[132:135], v168 offset:16
	ds_read_b128 v[184:187], v169 offset:16
	v_mfma_f32_16x16x32_f16 v[40:43], v[152:155], v[192:195], v[40:43]
	ds_read_b128 v[136:139], v168 offset:1040
	ds_read_b128 v[188:191], v169 offset:1040
	v_mfma_f32_16x16x32_f16 v[44:47], v[156:159], v[192:195], v[44:47]
	ds_read_b128 v[140:143], v168 offset:2064
	v_mfma_f32_16x16x32_f16 v[48:51], v[160:163], v[192:195], v[48:51]
	ds_read_b128 v[144:147], v168 offset:3088
	v_mfma_f32_16x16x32_f16 v[52:55], v[148:151], v[196:199], v[52:55]
	v_mfma_f32_16x16x32_f16 v[56:59], v[152:155], v[196:199], v[56:59]
	v_mfma_f32_16x16x32_f16 v[60:63], v[156:159], v[196:199], v[60:63]
	v_mfma_f32_16x16x32_f16 v[64:67], v[160:163], v[196:199], v[64:67]
	s_waitcnt lgkmcnt(0)
	s_mov_b32 s34, s65
	v_add_u32_e32 v169, s34, v164
	v_mfma_f32_16x16x32_f16 v[4:7], v[132:135], v[184:187], v[4:7]
	ds_read_b128 v[192:195], v169 offset:2064
	v_mfma_f32_16x16x32_f16 v[8:11], v[136:139], v[184:187], v[8:11]
	ds_read_b128 v[196:199], v169 offset:3088
	v_mfma_f32_16x16x32_f16 v[12:15], v[140:143], v[184:187], v[12:15]
	v_mfma_f32_16x16x32_f16 v[16:19], v[144:147], v[184:187], v[16:19]
	v_mfma_f32_16x16x32_f16 v[20:23], v[132:135], v[188:191], v[20:23]
	v_mfma_f32_16x16x32_f16 v[24:27], v[136:139], v[188:191], v[24:27]
	v_mfma_f32_16x16x32_f16 v[28:31], v[140:143], v[188:191], v[28:31]
	v_mfma_f32_16x16x32_f16 v[32:35], v[144:147], v[188:191], v[32:35]
	s_waitcnt vmcnt(0) lgkmcnt(0)
	s_barrier
	s_add_i32 s65, s34, 0x6000
	s_cmp_lg_u32 s34, 0x12000
	s_cselect_b32 s65, s65, 0
	v_add_u32_e32 v168, s65, v165
	v_add_u32_e32 v169, s65, v164
	v_mfma_f32_16x16x32_f16 v[36:39], v[132:135], v[192:195], v[36:39]
	ds_read_b128 v[148:151], v168 offset:16
	ds_read_b128 v[184:187], v169 offset:16
	v_mfma_f32_16x16x32_f16 v[40:43], v[136:139], v[192:195], v[40:43]
	ds_read_b128 v[152:155], v168 offset:1040
	ds_read_b128 v[188:191], v169 offset:1040
	v_mfma_f32_16x16x32_f16 v[44:47], v[140:143], v[192:195], v[44:47]
	ds_read_b128 v[156:159], v168 offset:2064
	v_mfma_f32_16x16x32_f16 v[48:51], v[144:147], v[192:195], v[48:51]
	ds_read_b128 v[160:163], v168 offset:3088
	v_mfma_f32_16x16x32_f16 v[52:55], v[132:135], v[196:199], v[52:55]
	v_mfma_f32_16x16x32_f16 v[56:59], v[136:139], v[196:199], v[56:59]
	v_mfma_f32_16x16x32_f16 v[60:63], v[140:143], v[196:199], v[60:63]
	v_mfma_f32_16x16x32_f16 v[64:67], v[144:147], v[196:199], v[64:67]
	s_waitcnt lgkmcnt(0)
	s_mov_b32 s34, s65
	v_add_u32_e32 v169, s34, v164
	v_mfma_f32_16x16x32_f16 v[4:7], v[148:151], v[184:187], v[4:7]
	ds_read_b128 v[192:195], v169 offset:2064
	v_mfma_f32_16x16x32_f16 v[8:11], v[152:155], v[184:187], v[8:11]
	ds_read_b128 v[196:199], v169 offset:3088
	v_mfma_f32_16x16x32_f16 v[12:15], v[156:159], v[184:187], v[12:15]
	v_mfma_f32_16x16x32_f16 v[16:19], v[160:163], v[184:187], v[16:19]
	v_mfma_f32_16x16x32_f16 v[20:23], v[148:151], v[188:191], v[20:23]
	v_mfma_f32_16x16x32_f16 v[24:27], v[152:155], v[188:191], v[24:27]
	v_mfma_f32_16x16x32_f16 v[28:31], v[156:159], v[188:191], v[28:31]
	v_mfma_f32_16x16x32_f16 v[32:35], v[160:163], v[188:191], v[32:35]
	s_waitcnt lgkmcnt(0)
	s_barrier
	v_mfma_f32_16x16x32_f16 v[36:39], v[148:151], v[192:195], v[36:39]
	v_mfma_f32_16x16x32_f16 v[40:43], v[152:155], v[192:195], v[40:43]
	v_mfma_f32_16x16x32_f16 v[44:47], v[156:159], v[192:195], v[44:47]
	v_mfma_f32_16x16x32_f16 v[48:51], v[160:163], v[192:195], v[48:51]
	v_mfma_f32_16x16x32_f16 v[52:55], v[148:151], v[196:199], v[52:55]
	v_mfma_f32_16x16x32_f16 v[56:59], v[152:155], v[196:199], v[56:59]
	v_mfma_f32_16x16x32_f16 v[60:63], v[156:159], v[196:199], v[60:63]
	v_mfma_f32_16x16x32_f16 v[64:67], v[160:163], v[196:199], v[64:67]
	s_sub_u32 s77, s35, 0x1000
	s_lshr_b32 s77, s77, 12
	s_add_u32 s77, s77, 1
	s_cmp_lt_u32 s35, 0x1000
	s_cselect_b32 s77, 0, s77
	s_mul_i32 s77, s77, 0x6000
	s_add_u32 s68, s46, s77
	s_addc_u32 s69, s47, 0
	s_add_u32 s68, s68, 0xfa2e600
	s_addc_u32 s69, s69, 0
	s_lshl_b32 s82, s35, 11
	s_add_u32 s80, s48, s82
	s_addc_u32 s81, s49, 0
	s_lshl_b32 s82, s30, 1
	s_add_u32 s80, s80, s82
	s_addc_u32 s81, s81, 0
	v_and_b32_e32 v172, 15, v200
	v_bfe_u32 v173, v200, 4, 2
	v_bfe_u32 v174, v200, 6, 1
	v_bfe_u32 v175, v200, 7, 2
	v_lshlrev_b32_e32 v176, 6, v174
	v_lshl_or_b32 v176, v173, 2, v176
	v_lshl_or_b32 v175, v175, 6, v172
	v_lshlrev_b32_e32 v175, 11, v175
	v_lshl_add_u32 v177, v176, 1, v175
	v_add_u32_e32 v176, s30, v176
	v_lshlrev_b32_e32 v176, 2, v176
	global_load_dwordx4 v[132:135], v176, s[68:69]
	global_load_dwordx4 v[136:139], v176, s[68:69] offset:64
	global_load_dwordx4 v[140:143], v176, s[68:69] offset:128
	global_load_dwordx4 v[144:147], v176, s[68:69] offset:192
	v_and_b32_e32 v172, 1, v173
	v_mul_u32_u24_e32 v172, 24, v172
	v_add_u32_e32 v177, v177, v172
	v_mov_b32_e32 v178, v177
	global_load_dwordx4 v[184:187], v178, s[80:81]
	global_load_dwordx4 v[188:191], v178, s[80:81] offset:64
	v_add_u32_e32 v178, 0x8000, v178
	global_load_dwordx4 v[192:195], v178, s[80:81]
	global_load_dwordx4 v[196:199], v178, s[80:81] offset:64
	s_waitcnt vmcnt(3)
	v_permlane16_swap_b32_e32 v184, v186
	v_permlane16_swap_b32_e32 v185, v187
	v_cvt_f32_f16_e32 v164, v184
	v_cvt_f32_f16_sdwa v165, v184 dst_sel:DWORD dst_unused:UNUSED_PAD src0_sel:WORD_1
	v_cvt_f32_f16_e32 v166, v185
	v_cvt_f32_f16_sdwa v167, v185 dst_sel:DWORD dst_unused:UNUSED_PAD src0_sel:WORD_1
	v_pk_mul_f32 v[164:165], v[164:165], s[84:85] op_sel_hi:[1,0]
	v_pk_mul_f32 v[166:167], v[166:167], s[84:85] op_sel_hi:[1,0]
	v_pk_fma_f32 v[4:5], v[4:5], v[132:133], v[164:165]
	v_pk_fma_f32 v[6:7], v[6:7], v[134:135], v[166:167]
	v_cvt_pk_f16_f32 v172, v4, v5
	v_cvt_pk_f16_f32 v173, v6, v7
	v_cvt_f32_f16_e32 v164, v186
	v_cvt_f32_f16_sdwa v165, v186 dst_sel:DWORD dst_unused:UNUSED_PAD src0_sel:WORD_1
	v_cvt_f32_f16_e32 v166, v187
	v_cvt_f32_f16_sdwa v167, v187 dst_sel:DWORD dst_unused:UNUSED_PAD src0_sel:WORD_1
	v_pk_mul_f32 v[164:165], v[164:165], s[84:85] op_sel_hi:[1,0]
	v_pk_mul_f32 v[166:167], v[166:167], s[84:85] op_sel_hi:[1,0]
	v_pk_fma_f32 v[8:9], v[8:9], v[136:137], v[164:165]
	v_pk_fma_f32 v[10:11], v[10:11], v[138:139], v[166:167]
	v_cvt_pk_f16_f32 v174, v8, v9
	v_cvt_pk_f16_f32 v175, v10, v11
	s_nop 1
	v_permlane16_swap_b32_e32 v172, v174
	v_permlane16_swap_b32_e32 v173, v175
	global_store_dwordx4 v177, v[172:175], s[80:81]
	s_waitcnt vmcnt(3)
	v_permlane16_swap_b32_e32 v188, v190
	v_permlane16_swap_b32_e32 v189, v191
	v_cvt_f32_f16_e32 v164, v188
	v_cvt_f32_f16_sdwa v165, v188 dst_sel:DWORD dst_unused:UNUSED_PAD src0_sel:WORD_1
	v_cvt_f32_f16_e32 v166, v189
	v_cvt_f32_f16_sdwa v167, v189 dst_sel:DWORD dst_unused:UNUSED_PAD src0_sel:WORD_1
	v_pk_mul_f32 v[164:165], v[164:165], s[84:85] op_sel_hi:[1,0]
	v_pk_mul_f32 v[166:167], v[166:167], s[84:85] op_sel_hi:[1,0]
	v_pk_fma_f32 v[12:13], v[12:13], v[140:141], v[164:165]
	v_pk_fma_f32 v[14:15], v[14:15], v[142:143], v[166:167]
	v_cvt_pk_f16_f32 v228, v12, v13
	v_cvt_pk_f16_f32 v229, v14, v15
	v_cvt_f32_f16_e32 v164, v190
	v_cvt_f32_f16_sdwa v165, v190 dst_sel:DWORD dst_unused:UNUSED_PAD src0_sel:WORD_1
	v_cvt_f32_f16_e32 v166, v191
	v_cvt_f32_f16_sdwa v167, v191 dst_sel:DWORD dst_unused:UNUSED_PAD src0_sel:WORD_1
	v_pk_mul_f32 v[164:165], v[164:165], s[84:85] op_sel_hi:[1,0]
	v_pk_mul_f32 v[166:167], v[166:167], s[84:85] op_sel_hi:[1,0]
	v_pk_fma_f32 v[16:17], v[16:17], v[144:145], v[164:165]
	v_pk_fma_f32 v[18:19], v[18:19], v[146:147], v[166:167]
	v_cvt_pk_f16_f32 v230, v16, v17
	v_cvt_pk_f16_f32 v231, v18, v19
	s_nop 1
	v_permlane16_swap_b32_e32 v228, v230
	v_permlane16_swap_b32_e32 v229, v231
	global_store_dwordx4 v177, v[228:231], s[80:81] offset:64
	v_add_u32_e32 v177, 0x8000, v177
	v_add_u32_e32 v178, 0x8000, v178
	global_load_dwordx4 v[184:187], v178, s[80:81]
	global_load_dwordx4 v[188:191], v178, s[80:81] offset:64
	s_waitcnt vmcnt(5)
	v_permlane16_swap_b32_e32 v192, v194
	v_permlane16_swap_b32_e32 v193, v195
	v_cvt_f32_f16_e32 v164, v192
	v_cvt_f32_f16_sdwa v165, v192 dst_sel:DWORD dst_unused:UNUSED_PAD src0_sel:WORD_1
	v_cvt_f32_f16_e32 v166, v193
	v_cvt_f32_f16_sdwa v167, v193 dst_sel:DWORD dst_unused:UNUSED_PAD src0_sel:WORD_1
	v_pk_mul_f32 v[164:165], v[164:165], s[84:85] op_sel_hi:[1,0]
	v_pk_mul_f32 v[166:167], v[166:167], s[84:85] op_sel_hi:[1,0]
	v_pk_fma_f32 v[20:21], v[20:21], v[132:133], v[164:165]
	v_pk_fma_f32 v[22:23], v[22:23], v[134:135], v[166:167]
	v_cvt_pk_f16_f32 v172, v20, v21
	v_cvt_pk_f16_f32 v173, v22, v23
	v_cvt_f32_f16_e32 v164, v194
	v_cvt_f32_f16_sdwa v165, v194 dst_sel:DWORD dst_unused:UNUSED_PAD src0_sel:WORD_1
	v_cvt_f32_f16_e32 v166, v195
	v_cvt_f32_f16_sdwa v167, v195 dst_sel:DWORD dst_unused:UNUSED_PAD src0_sel:WORD_1
	v_pk_mul_f32 v[164:165], v[164:165], s[84:85] op_sel_hi:[1,0]
	v_pk_mul_f32 v[166:167], v[166:167], s[84:85] op_sel_hi:[1,0]
	v_pk_fma_f32 v[24:25], v[24:25], v[136:137], v[164:165]
	v_pk_fma_f32 v[26:27], v[26:27], v[138:139], v[166:167]
	v_cvt_pk_f16_f32 v174, v24, v25
	v_cvt_pk_f16_f32 v175, v26, v27
	s_nop 1
	v_permlane16_swap_b32_e32 v172, v174
	v_permlane16_swap_b32_e32 v173, v175
	global_store_dwordx4 v177, v[172:175], s[80:81]
	s_waitcnt vmcnt(5)
	v_permlane16_swap_b32_e32 v196, v198
	v_permlane16_swap_b32_e32 v197, v199
	v_cvt_f32_f16_e32 v164, v196
	v_cvt_f32_f16_sdwa v165, v196 dst_sel:DWORD dst_unused:UNUSED_PAD src0_sel:WORD_1
	v_cvt_f32_f16_e32 v166, v197
	v_cvt_f32_f16_sdwa v167, v197 dst_sel:DWORD dst_unused:UNUSED_PAD src0_sel:WORD_1
	v_pk_mul_f32 v[164:165], v[164:165], s[84:85] op_sel_hi:[1,0]
	v_pk_mul_f32 v[166:167], v[166:167], s[84:85] op_sel_hi:[1,0]
	v_pk_fma_f32 v[28:29], v[28:29], v[140:141], v[164:165]
	v_pk_fma_f32 v[30:31], v[30:31], v[142:143], v[166:167]
	v_cvt_pk_f16_f32 v228, v28, v29
	v_cvt_pk_f16_f32 v229, v30, v31
	v_cvt_f32_f16_e32 v164, v198
	v_cvt_f32_f16_sdwa v165, v198 dst_sel:DWORD dst_unused:UNUSED_PAD src0_sel:WORD_1
	v_cvt_f32_f16_e32 v166, v199
	v_cvt_f32_f16_sdwa v167, v199 dst_sel:DWORD dst_unused:UNUSED_PAD src0_sel:WORD_1
	v_pk_mul_f32 v[164:165], v[164:165], s[84:85] op_sel_hi:[1,0]
	v_pk_mul_f32 v[166:167], v[166:167], s[84:85] op_sel_hi:[1,0]
	v_pk_fma_f32 v[32:33], v[32:33], v[144:145], v[164:165]
	v_pk_fma_f32 v[34:35], v[34:35], v[146:147], v[166:167]
	v_cvt_pk_f16_f32 v230, v32, v33
	v_cvt_pk_f16_f32 v231, v34, v35
	s_nop 1
	v_permlane16_swap_b32_e32 v228, v230
	v_permlane16_swap_b32_e32 v229, v231
	global_store_dwordx4 v177, v[228:231], s[80:81] offset:64
	v_add_u32_e32 v177, 0x8000, v177
	v_add_u32_e32 v178, 0x8000, v178
	global_load_dwordx4 v[192:195], v178, s[80:81]
	global_load_dwordx4 v[196:199], v178, s[80:81] offset:64
	s_waitcnt vmcnt(5)
	v_permlane16_swap_b32_e32 v184, v186
	v_permlane16_swap_b32_e32 v185, v187
	v_cvt_f32_f16_e32 v164, v184
	v_cvt_f32_f16_sdwa v165, v184 dst_sel:DWORD dst_unused:UNUSED_PAD src0_sel:WORD_1
	v_cvt_f32_f16_e32 v166, v185
	v_cvt_f32_f16_sdwa v167, v185 dst_sel:DWORD dst_unused:UNUSED_PAD src0_sel:WORD_1
	v_pk_mul_f32 v[164:165], v[164:165], s[84:85] op_sel_hi:[1,0]
	v_pk_mul_f32 v[166:167], v[166:167], s[84:85] op_sel_hi:[1,0]
	v_pk_fma_f32 v[36:37], v[36:37], v[132:133], v[164:165]
	v_pk_fma_f32 v[38:39], v[38:39], v[134:135], v[166:167]
	v_cvt_pk_f16_f32 v172, v36, v37
	v_cvt_pk_f16_f32 v173, v38, v39
	v_cvt_f32_f16_e32 v164, v186
	v_cvt_f32_f16_sdwa v165, v186 dst_sel:DWORD dst_unused:UNUSED_PAD src0_sel:WORD_1
	v_cvt_f32_f16_e32 v166, v187
	v_cvt_f32_f16_sdwa v167, v187 dst_sel:DWORD dst_unused:UNUSED_PAD src0_sel:WORD_1
	v_pk_mul_f32 v[164:165], v[164:165], s[84:85] op_sel_hi:[1,0]
	v_pk_mul_f32 v[166:167], v[166:167], s[84:85] op_sel_hi:[1,0]
	v_pk_fma_f32 v[40:41], v[40:41], v[136:137], v[164:165]
	v_pk_fma_f32 v[42:43], v[42:43], v[138:139], v[166:167]
	v_cvt_pk_f16_f32 v174, v40, v41
	v_cvt_pk_f16_f32 v175, v42, v43
	s_nop 1
	v_permlane16_swap_b32_e32 v172, v174
	v_permlane16_swap_b32_e32 v173, v175
	global_store_dwordx4 v177, v[172:175], s[80:81]
	s_waitcnt vmcnt(5)
	v_permlane16_swap_b32_e32 v188, v190
	v_permlane16_swap_b32_e32 v189, v191
	v_cvt_f32_f16_e32 v164, v188
	v_cvt_f32_f16_sdwa v165, v188 dst_sel:DWORD dst_unused:UNUSED_PAD src0_sel:WORD_1
	v_cvt_f32_f16_e32 v166, v189
	v_cvt_f32_f16_sdwa v167, v189 dst_sel:DWORD dst_unused:UNUSED_PAD src0_sel:WORD_1
	v_pk_mul_f32 v[164:165], v[164:165], s[84:85] op_sel_hi:[1,0]
	v_pk_mul_f32 v[166:167], v[166:167], s[84:85] op_sel_hi:[1,0]
	v_pk_fma_f32 v[44:45], v[44:45], v[140:141], v[164:165]
	v_pk_fma_f32 v[46:47], v[46:47], v[142:143], v[166:167]
	v_cvt_pk_f16_f32 v228, v44, v45
	v_cvt_pk_f16_f32 v229, v46, v47
	v_cvt_f32_f16_e32 v164, v190
	v_cvt_f32_f16_sdwa v165, v190 dst_sel:DWORD dst_unused:UNUSED_PAD src0_sel:WORD_1
	v_cvt_f32_f16_e32 v166, v191
	v_cvt_f32_f16_sdwa v167, v191 dst_sel:DWORD dst_unused:UNUSED_PAD src0_sel:WORD_1
	v_pk_mul_f32 v[164:165], v[164:165], s[84:85] op_sel_hi:[1,0]
	v_pk_mul_f32 v[166:167], v[166:167], s[84:85] op_sel_hi:[1,0]
	v_pk_fma_f32 v[48:49], v[48:49], v[144:145], v[164:165]
	v_pk_fma_f32 v[50:51], v[50:51], v[146:147], v[166:167]
	v_cvt_pk_f16_f32 v230, v48, v49
	v_cvt_pk_f16_f32 v231, v50, v51
	s_nop 1
	v_permlane16_swap_b32_e32 v228, v230
	v_permlane16_swap_b32_e32 v229, v231
	global_store_dwordx4 v177, v[228:231], s[80:81] offset:64
	v_add_u32_e32 v177, 0x8000, v177
	s_waitcnt vmcnt(3)
	v_permlane16_swap_b32_e32 v192, v194
	v_permlane16_swap_b32_e32 v193, v195
	v_cvt_f32_f16_e32 v164, v192
	v_cvt_f32_f16_sdwa v165, v192 dst_sel:DWORD dst_unused:UNUSED_PAD src0_sel:WORD_1
	v_cvt_f32_f16_e32 v166, v193
	v_cvt_f32_f16_sdwa v167, v193 dst_sel:DWORD dst_unused:UNUSED_PAD src0_sel:WORD_1
	v_pk_mul_f32 v[164:165], v[164:165], s[84:85] op_sel_hi:[1,0]
	v_pk_mul_f32 v[166:167], v[166:167], s[84:85] op_sel_hi:[1,0]
	v_pk_fma_f32 v[52:53], v[52:53], v[132:133], v[164:165]
	v_pk_fma_f32 v[54:55], v[54:55], v[134:135], v[166:167]
	v_cvt_pk_f16_f32 v172, v52, v53
	v_cvt_pk_f16_f32 v173, v54, v55
	v_cvt_f32_f16_e32 v164, v194
	v_cvt_f32_f16_sdwa v165, v194 dst_sel:DWORD dst_unused:UNUSED_PAD src0_sel:WORD_1
	v_cvt_f32_f16_e32 v166, v195
	v_cvt_f32_f16_sdwa v167, v195 dst_sel:DWORD dst_unused:UNUSED_PAD src0_sel:WORD_1
	v_pk_mul_f32 v[164:165], v[164:165], s[84:85] op_sel_hi:[1,0]
	v_pk_mul_f32 v[166:167], v[166:167], s[84:85] op_sel_hi:[1,0]
	v_pk_fma_f32 v[56:57], v[56:57], v[136:137], v[164:165]
	v_pk_fma_f32 v[58:59], v[58:59], v[138:139], v[166:167]
	v_cvt_pk_f16_f32 v174, v56, v57
	v_cvt_pk_f16_f32 v175, v58, v59
	s_nop 1
	v_permlane16_swap_b32_e32 v172, v174
	v_permlane16_swap_b32_e32 v173, v175
	global_store_dwordx4 v177, v[172:175], s[80:81]
	s_waitcnt vmcnt(3)
	v_permlane16_swap_b32_e32 v196, v198
	v_permlane16_swap_b32_e32 v197, v199
	v_cvt_f32_f16_e32 v164, v196
	v_cvt_f32_f16_sdwa v165, v196 dst_sel:DWORD dst_unused:UNUSED_PAD src0_sel:WORD_1
	v_cvt_f32_f16_e32 v166, v197
	v_cvt_f32_f16_sdwa v167, v197 dst_sel:DWORD dst_unused:UNUSED_PAD src0_sel:WORD_1
	v_pk_mul_f32 v[164:165], v[164:165], s[84:85] op_sel_hi:[1,0]
	v_pk_mul_f32 v[166:167], v[166:167], s[84:85] op_sel_hi:[1,0]
	v_pk_fma_f32 v[60:61], v[60:61], v[140:141], v[164:165]
	v_pk_fma_f32 v[62:63], v[62:63], v[142:143], v[166:167]
	v_cvt_pk_f16_f32 v228, v60, v61
	v_cvt_pk_f16_f32 v229, v62, v63
	v_cvt_f32_f16_e32 v164, v198
	v_cvt_f32_f16_sdwa v165, v198 dst_sel:DWORD dst_unused:UNUSED_PAD src0_sel:WORD_1
	v_cvt_f32_f16_e32 v166, v199
	v_cvt_f32_f16_sdwa v167, v199 dst_sel:DWORD dst_unused:UNUSED_PAD src0_sel:WORD_1
	v_pk_mul_f32 v[164:165], v[164:165], s[84:85] op_sel_hi:[1,0]
	v_pk_mul_f32 v[166:167], v[166:167], s[84:85] op_sel_hi:[1,0]
	v_pk_fma_f32 v[64:65], v[64:65], v[144:145], v[164:165]
	v_pk_fma_f32 v[66:67], v[66:67], v[146:147], v[166:167]
	v_cvt_pk_f16_f32 v230, v64, v65
	v_cvt_pk_f16_f32 v231, v66, v67
	s_nop 1
	v_permlane16_swap_b32_e32 v228, v230
	v_permlane16_swap_b32_e32 v229, v231
	global_store_dwordx4 v177, v[228:231], s[80:81] offset:64
	s_nop 1
	s_addk_i32 s24, 0x1000
	s_add_i32 s28, s25, 32
	s_cmp_gt_u32 s25, 31
	s_mov_b32 s25, s28
	s_cbranch_scc1 .LBB0_88
	s_branch .LBB0_72

.LBB0_760:
	s_andn2_b64 vcc, exec, s[28:29]
	s_cbranch_vccnz .LBB0_853
	v_readlane_b32 s24, v236, 3
	v_readlane_b32 s25, v236, 4
	s_andn2_b64 vcc, exec, s[24:25]
	s_cbranch_vccnz .LBB0_814
	s_add_u32 s26, s44, 0xaa08000
	s_addc_u32 s27, s45, 0
	v_readlane_b32 s24, v236, 5
	v_readlane_b32 s25, v236, 9
	s_branch .LBB0_764
.LBB0_764:
	s_and_b32 s28, s25, 56
	s_or_b32 s29, s28, s83
	s_lshl_b32 s35, s29, 8
	s_cmp_gt_u32 s28, 39
	s_mov_b64 s[28:29], -1
	s_cbranch_scc0 .LBB0_766
	s_add_i32 s90, s35, 0xffffd800
	s_mov_b64 s[28:29], 0

.LBB0_768:
	s_waitcnt lgkmcnt(0)
	s_lshl_b64 s[36:37], s[90:91], 13
	s_add_u32 s36, s36, s28
	s_addc_u32 s37, s37, s29
	s_and_b32 s30, s25, 7
	s_lshl_b32 s30, s30, 7
	s_lshl_b32 s54, s30, 13
	s_add_u32 s50, s48, s54
	s_addc_u32 s51, s49, 0
	v_readfirstlane_b32 s54, v200
	s_lshr_b32 s54, s54, 6
	s_lshl_b32 s31, s54, 11
	s_add_u32 s31, s31, 16
	s_lshl_b32 s32, s54, 10
	s_add_u32 s32, s32, 0x4010
	s_lshl_b32 s54, s54, 17
	s_add_u32 s50, s50, s54
	s_addc_u32 s51, s51, 0
	s_lshl_b32 s54, s54, 1
	s_add_u32 s36, s36, s54
	s_addc_u32 s37, s37, 0
	v_bfe_u32 v173, v200, 4, 2
	v_sub_u32_e32 v173, 0, v173
	v_and_b32_e32 v173, 3, v173
	v_and_b32_e32 v172, 3, v200
	v_xor_b32_e32 v172, v172, v173
	v_bfe_u32 v173, v200, 2, 4
	v_lshlrev_b32_e32 v173, 13, v173
	v_lshl_or_b32 v170, v172, 4, v173
	v_add_u32_e32 v171, 0x20000, v170
	v_bfe_u32 v172, v200, 2, 2
	v_sub_u32_e32 v172, 0, v172
	v_and_b32_e32 v172, 3, v172
	v_bfe_u32 v173, v200, 4, 2
	v_xor_b32_e32 v172, v172, v173
	v_and_b32_e32 v173, 15, v200
	v_bfe_u32 v174, v200, 7, 2
	v_lshl_or_b32 v174, v174, 6, v173
	v_lshlrev_b32_e32 v174, 6, v174
	v_lshl_or_b32 v164, v172, 4, v174
	v_bfe_u32 v174, v200, 6, 1
	v_lshl_or_b32 v174, v174, 6, v173
	v_lshlrev_b32_e32 v174, 6, v174
	v_lshl_or_b32 v165, v172, 4, v174
	v_add_u32_e32 v165, 0x4000, v165
	v_bfe_u32 v172, v200, 6, 1
	v_bfe_u32 v173, v200, 4, 2
	v_lshlrev_b32_e32 v172, 6, v172
	v_lshl_or_b32 v172, v173, 2, v172
	v_add_u32_e32 v172, s30, v172
	v_lshlrev_b32_e32 v172, 2, v172
	global_load_dwordx4 v[132:135], v172, s[42:43]
	global_load_dwordx4 v[136:139], v172, s[42:43] offset:64
	global_load_dwordx4 v[140:143], v172, s[42:43] offset:128
	global_load_dwordx4 v[144:147], v172, s[42:43] offset:192
	s_mov_b32 s52, 0x0
	s_add_u32 m0, s31, s52
	s_nop 0
	global_load_lds_dwordx4 v170, s[36:37]
	s_add_u32 m0, s31, s52
	s_add_u32 m0, m0, 0x400
	s_nop 0
	global_load_lds_dwordx4 v171, s[36:37]
	s_add_u32 m0, s32, s52
	s_nop 0
	global_load_lds_dwordx4 v170, s[50:51]
	s_add_u32 s36, s36, 64
	s_addc_u32 s37, s37, 0
	s_add_u32 s50, s50, 64
	s_addc_u32 s51, s51, 0
	s_mov_b32 s52, 0x6000
	s_add_u32 m0, s31, s52
	s_nop 0
	global_load_lds_dwordx4 v170, s[36:37]
	s_add_u32 m0, s31, s52
	s_add_u32 m0, m0, 0x400
	s_nop 0
	global_load_lds_dwordx4 v171, s[36:37]
	s_add_u32 m0, s32, s52
	s_nop 0
	global_load_lds_dwordx4 v170, s[50:51]
	s_add_u32 s36, s36, 64
	s_addc_u32 s37, s37, 0
	s_add_u32 s50, s50, 64
	s_addc_u32 s51, s51, 0
	s_mov_b32 s52, 0xc000
	s_add_u32 m0, s31, s52
	s_nop 0
	global_load_lds_dwordx4 v170, s[36:37]
	s_add_u32 m0, s31, s52
	s_add_u32 m0, m0, 0x400
	s_nop 0
	global_load_lds_dwordx4 v171, s[36:37]
	s_add_u32 m0, s32, s52
	s_nop 0
	global_load_lds_dwordx4 v170, s[50:51]
	s_add_u32 s36, s36, 64
	s_addc_u32 s37, s37, 0
	s_add_u32 s50, s50, 64
	s_addc_u32 s51, s51, 0
	s_mov_b32 s52, 0x12000
	s_add_u32 m0, s31, s52
	s_nop 0
	global_load_lds_dwordx4 v170, s[36:37]
	s_add_u32 m0, s31, s52
	s_add_u32 m0, m0, 0x400
	s_nop 0
	global_load_lds_dwordx4 v171, s[36:37]
	s_add_u32 m0, s32, s52
	s_nop 0
	global_load_lds_dwordx4 v170, s[50:51]
	s_add_u32 s36, s36, 64
	s_addc_u32 s37, s37, 0
	s_add_u32 s50, s50, 64
	s_addc_u32 s51, s51, 0
	s_waitcnt vmcnt(12)
	v_mov_b32_e32 v4, v132
	v_mov_b32_e32 v5, v133
	v_mov_b32_e32 v6, v134
	v_mov_b32_e32 v7, v135
	v_mov_b32_e32 v8, v136
	v_mov_b32_e32 v9, v137
	v_mov_b32_e32 v10, v138
	v_mov_b32_e32 v11, v139
	v_mov_b32_e32 v12, v140
	v_mov_b32_e32 v13, v141
	v_mov_b32_e32 v14, v142
	v_mov_b32_e32 v15, v143
	v_mov_b32_e32 v16, v144
	v_mov_b32_e32 v17, v145
	v_mov_b32_e32 v18, v146
	v_mov_b32_e32 v19, v147
	v_mov_b32_e32 v20, v132
	v_mov_b32_e32 v21, v133
	v_mov_b32_e32 v22, v134
	v_mov_b32_e32 v23, v135
	v_mov_b32_e32 v24, v136
	v_mov_b32_e32 v25, v137
	v_mov_b32_e32 v26, v138
	v_mov_b32_e32 v27, v139
	v_mov_b32_e32 v28, v140
	v_mov_b32_e32 v29, v141
	v_mov_b32_e32 v30, v142
	v_mov_b32_e32 v31, v143
	v_mov_b32_e32 v32, v144
	v_mov_b32_e32 v33, v145
	v_mov_b32_e32 v34, v146
	v_mov_b32_e32 v35, v147
	v_mov_b32_e32 v36, v132
	v_mov_b32_e32 v37, v133
	v_mov_b32_e32 v38, v134
	v_mov_b32_e32 v39, v135
	v_mov_b32_e32 v40, v136
	v_mov_b32_e32 v41, v137
	v_mov_b32_e32 v42, v138
	v_mov_b32_e32 v43, v139
	v_mov_b32_e32 v44, v140
	v_mov_b32_e32 v45, v141
	v_mov_b32_e32 v46, v142
	v_mov_b32_e32 v47, v143
	v_mov_b32_e32 v48, v144
	v_mov_b32_e32 v49, v145
	v_mov_b32_e32 v50, v146
	v_mov_b32_e32 v51, v147
	v_mov_b32_e32 v52, v132
	v_mov_b32_e32 v53, v133
	v_mov_b32_e32 v54, v134
	v_mov_b32_e32 v55, v135
	v_mov_b32_e32 v56, v136
	v_mov_b32_e32 v57, v137
	v_mov_b32_e32 v58, v138
	v_mov_b32_e32 v59, v139
	v_mov_b32_e32 v60, v140
	v_mov_b32_e32 v61, v141
	v_mov_b32_e32 v62, v142
	v_mov_b32_e32 v63, v143
	v_mov_b32_e32 v64, v144
	v_mov_b32_e32 v65, v145
	v_mov_b32_e32 v66, v146
	v_mov_b32_e32 v67, v147
	s_waitcnt vmcnt(9)
	s_barrier
	s_mov_b32 s34, 0
	s_mov_b32 s53, 0
	s_nop 1
	v_add_u32_e32 v168, s34, v165
	v_add_u32_e32 v169, s34, v164
	ds_read_b128 v[132:135], v168 offset:16
	ds_read_b128 v[136:139], v168 offset:1040
	ds_read_b128 v[140:143], v168 offset:2064
	ds_read_b128 v[144:147], v168 offset:3088
	ds_read_b128 v[184:187], v169 offset:16
	ds_read_b128 v[188:191], v169 offset:1040
	s_waitcnt lgkmcnt(0)
.Lt_mlp2av:
	v_add_u32_e32 v169, s34, v164
	v_mfma_f32_16x16x32_f16 v[4:7], v[132:135], v[184:187], v[4:7]
	ds_read_b128 v[192:195], v169 offset:2064
	v_mfma_f32_16x16x32_f16 v[8:11], v[136:139], v[184:187], v[8:11]
	ds_read_b128 v[196:199], v169 offset:3088
	v_mfma_f32_16x16x32_f16 v[12:15], v[140:143], v[184:187], v[12:15]
	v_mfma_f32_16x16x32_f16 v[16:19], v[144:147], v[184:187], v[16:19]
	v_mfma_f32_16x16x32_f16 v[20:23], v[132:135], v[188:191], v[20:23]
	v_mfma_f32_16x16x32_f16 v[24:27], v[136:139], v[188:191], v[24:27]
	v_mfma_f32_16x16x32_f16 v[28:31], v[140:143], v[188:191], v[28:31]
	v_mfma_f32_16x16x32_f16 v[32:35], v[144:147], v[188:191], v[32:35]
	s_waitcnt vmcnt(6) lgkmcnt(0)
	s_barrier
	s_add_i32 s52, s34, 0x6000
	s_cmp_lg_u32 s34, 0x12000
	s_cselect_b32 s52, s52, 0
	v_add_u32_e32 v168, s52, v165
	v_add_u32_e32 v169, s52, v164
	v_mfma_f32_16x16x32_f16 v[36:39], v[132:135], v[192:195], v[36:39]
	ds_read_b128 v[148:151], v168 offset:16
	ds_read_b128 v[184:187], v169 offset:16
	v_mfma_f32_16x16x32_f16 v[40:43], v[136:139], v[192:195], v[40:43]
	ds_read_b128 v[152:155], v168 offset:1040
	ds_read_b128 v[188:191], v169 offset:1040
	v_mfma_f32_16x16x32_f16 v[44:47], v[140:143], v[192:195], v[44:47]
	ds_read_b128 v[156:159], v168 offset:2064
	v_mfma_f32_16x16x32_f16 v[48:51], v[144:147], v[192:195], v[48:51]
	ds_read_b128 v[160:163], v168 offset:3088
	v_mfma_f32_16x16x32_f16 v[52:55], v[132:135], v[196:199], v[52:55]
	s_add_u32 m0, s31, s34
	s_nop 0
	global_load_lds_dwordx4 v170, s[36:37]
	v_mfma_f32_16x16x32_f16 v[56:59], v[136:139], v[196:199], v[56:59]
	s_add_u32 m0, s31, s34
	s_add_u32 m0, m0, 0x400
	s_nop 0
	global_load_lds_dwordx4 v171, s[36:37]
	v_mfma_f32_16x16x32_f16 v[60:63], v[140:143], v[196:199], v[60:63]
	s_add_u32 m0, s32, s34
	s_nop 0
	global_load_lds_dwordx4 v170, s[50:51]
	v_mfma_f32_16x16x32_f16 v[64:67], v[144:147], v[196:199], v[64:67]
	s_waitcnt lgkmcnt(0)
	s_mov_b32 s34, s52
	s_add_u32 s36, s36, 64
	s_addc_u32 s37, s37, 0
	s_add_u32 s50, s50, 64
	s_addc_u32 s51, s51, 0
	v_add_u32_e32 v169, s34, v164
	v_mfma_f32_16x16x32_f16 v[4:7], v[148:151], v[184:187], v[4:7]
	ds_read_b128 v[192:195], v169 offset:2064
	v_mfma_f32_16x16x32_f16 v[8:11], v[152:155], v[184:187], v[8:11]
	ds_read_b128 v[196:199], v169 offset:3088
	v_mfma_f32_16x16x32_f16 v[12:15], v[156:159], v[184:187], v[12:15]
	v_mfma_f32_16x16x32_f16 v[16:19], v[160:163], v[184:187], v[16:19]
	v_mfma_f32_16x16x32_f16 v[20:23], v[148:151], v[188:191], v[20:23]
	v_mfma_f32_16x16x32_f16 v[24:27], v[152:155], v[188:191], v[24:27]
	v_mfma_f32_16x16x32_f16 v[28:31], v[156:159], v[188:191], v[28:31]
	v_mfma_f32_16x16x32_f16 v[32:35], v[160:163], v[188:191], v[32:35]
	s_waitcnt vmcnt(6) lgkmcnt(0)
	s_barrier
	s_add_i32 s52, s34, 0x6000
	s_cmp_lg_u32 s34, 0x12000
	s_cselect_b32 s52, s52, 0
	v_add_u32_e32 v168, s52, v165
	v_add_u32_e32 v169, s52, v164
	v_mfma_f32_16x16x32_f16 v[36:39], v[148:151], v[192:195], v[36:39]
	ds_read_b128 v[132:135], v168 offset:16
	ds_read_b128 v[184:187], v169 offset:16
	v_mfma_f32_16x16x32_f16 v[40:43], v[152:155], v[192:195], v[40:43]
	ds_read_b128 v[136:139], v168 offset:1040
	ds_read_b128 v[188:191], v169 offset:1040
	v_mfma_f32_16x16x32_f16 v[44:47], v[156:159], v[192:195], v[44:47]
	ds_read_b128 v[140:143], v168 offset:2064
	v_mfma_f32_16x16x32_f16 v[48:51], v[160:163], v[192:195], v[48:51]
	ds_read_b128 v[144:147], v168 offset:3088
	v_mfma_f32_16x16x32_f16 v[52:55], v[148:151], v[196:199], v[52:55]
	s_add_u32 m0, s31, s34
	s_nop 0
	global_load_lds_dwordx4 v170, s[36:37]
	v_mfma_f32_16x16x32_f16 v[56:59], v[152:155], v[196:199], v[56:59]
	s_add_u32 m0, s31, s34
	s_add_u32 m0, m0, 0x400
	s_nop 0
	global_load_lds_dwordx4 v171, s[36:37]
	v_mfma_f32_16x16x32_f16 v[60:63], v[156:159], v[196:199], v[60:63]
	s_add_u32 m0, s32, s34
	s_nop 0
	global_load_lds_dwordx4 v170, s[50:51]
	v_mfma_f32_16x16x32_f16 v[64:67], v[160:163], v[196:199], v[64:67]
	s_waitcnt lgkmcnt(0)
	s_mov_b32 s34, s52
	s_add_u32 s36, s36, 64
	s_addc_u32 s37, s37, 0
	s_add_u32 s50, s50, 64
	s_addc_u32 s51, s51, 0
	s_add_i32 s53, s53, 2
	s_cmp_lt_u32 s53, 124
	s_cbranch_scc1 .Lt_mlp2av
	v_add_u32_e32 v169, s34, v164
	v_mfma_f32_16x16x32_f16 v[4:7], v[132:135], v[184:187], v[4:7]
	ds_read_b128 v[192:195], v169 offset:2064
	v_mfma_f32_16x16x32_f16 v[8:11], v[136:139], v[184:187], v[8:11]
	ds_read_b128 v[196:199], v169 offset:3088
	v_mfma_f32_16x16x32_f16 v[12:15], v[140:143], v[184:187], v[12:15]
	v_mfma_f32_16x16x32_f16 v[16:19], v[144:147], v[184:187], v[16:19]
	v_mfma_f32_16x16x32_f16 v[20:23], v[132:135], v[188:191], v[20:23]
	v_mfma_f32_16x16x32_f16 v[24:27], v[136:139], v[188:191], v[24:27]
	v_mfma_f32_16x16x32_f16 v[28:31], v[140:143], v[188:191], v[28:31]
	v_mfma_f32_16x16x32_f16 v[32:35], v[144:147], v[188:191], v[32:35]
	s_waitcnt vmcnt(6) lgkmcnt(0)
	s_barrier
	s_add_i32 s52, s34, 0x6000
	s_cmp_lg_u32 s34, 0x12000
	s_cselect_b32 s52, s52, 0
	v_add_u32_e32 v168, s52, v165
	v_add_u32_e32 v169, s52, v164
	v_mfma_f32_16x16x32_f16 v[36:39], v[132:135], v[192:195], v[36:39]
	ds_read_b128 v[148:151], v168 offset:16
	ds_read_b128 v[184:187], v169 offset:16
	v_mfma_f32_16x16x32_f16 v[40:43], v[136:139], v[192:195], v[40:43]
	ds_read_b128 v[152:155], v168 offset:1040
	ds_read_b128 v[188:191], v169 offset:1040
	v_mfma_f32_16x16x32_f16 v[44:47], v[140:143], v[192:195], v[44:47]
	ds_read_b128 v[156:159], v168 offset:2064
	v_mfma_f32_16x16x32_f16 v[48:51], v[144:147], v[192:195], v[48:51]
	ds_read_b128 v[160:163], v168 offset:3088
	v_mfma_f32_16x16x32_f16 v[52:55], v[132:135], v[196:199], v[52:55]
	v_mfma_f32_16x16x32_f16 v[56:59], v[136:139], v[196:199], v[56:59]
	v_mfma_f32_16x16x32_f16 v[60:63], v[140:143], v[196:199], v[60:63]
	v_mfma_f32_16x16x32_f16 v[64:67], v[144:147], v[196:199], v[64:67]
	s_waitcnt lgkmcnt(0)
	s_mov_b32 s34, s52
	v_add_u32_e32 v169, s34, v164
	v_mfma_f32_16x16x32_f16 v[4:7], v[148:151], v[184:187], v[4:7]
	ds_read_b128 v[192:195], v169 offset:2064
	v_mfma_f32_16x16x32_f16 v[8:11], v[152:155], v[184:187], v[8:11]
	ds_read_b128 v[196:199], v169 offset:3088
	v_mfma_f32_16x16x32_f16 v[12:15], v[156:159], v[184:187], v[12:15]
	v_mfma_f32_16x16x32_f16 v[16:19], v[160:163], v[184:187], v[16:19]
	v_mfma_f32_16x16x32_f16 v[20:23], v[148:151], v[188:191], v[20:23]
	v_mfma_f32_16x16x32_f16 v[24:27], v[152:155], v[188:191], v[24:27]
	v_mfma_f32_16x16x32_f16 v[28:31], v[156:159], v[188:191], v[28:31]
	v_mfma_f32_16x16x32_f16 v[32:35], v[160:163], v[188:191], v[32:35]
	s_waitcnt vmcnt(3) lgkmcnt(0)
	s_barrier
	s_add_i32 s52, s34, 0x6000
	s_cmp_lg_u32 s34, 0x12000
	s_cselect_b32 s52, s52, 0
	v_add_u32_e32 v168, s52, v165
	v_add_u32_e32 v169, s52, v164
	v_mfma_f32_16x16x32_f16 v[36:39], v[148:151], v[192:195], v[36:39]
	ds_read_b128 v[132:135], v168 offset:16
	ds_read_b128 v[184:187], v169 offset:16
	v_mfma_f32_16x16x32_f16 v[40:43], v[152:155], v[192:195], v[40:43]
	ds_read_b128 v[136:139], v168 offset:1040
	ds_read_b128 v[188:191], v169 offset:1040
	v_mfma_f32_16x16x32_f16 v[44:47], v[156:159], v[192:195], v[44:47]
	ds_read_b128 v[140:143], v168 offset:2064
	v_mfma_f32_16x16x32_f16 v[48:51], v[160:163], v[192:195], v[48:51]
	ds_read_b128 v[144:147], v168 offset:3088
	v_mfma_f32_16x16x32_f16 v[52:55], v[148:151], v[196:199], v[52:55]
	v_mfma_f32_16x16x32_f16 v[56:59], v[152:155], v[196:199], v[56:59]
	v_mfma_f32_16x16x32_f16 v[60:63], v[156:159], v[196:199], v[60:63]
	v_mfma_f32_16x16x32_f16 v[64:67], v[160:163], v[196:199], v[64:67]
	s_waitcnt lgkmcnt(0)
	s_mov_b32 s34, s52
	v_add_u32_e32 v169, s34, v164
	v_mfma_f32_16x16x32_f16 v[4:7], v[132:135], v[184:187], v[4:7]
	ds_read_b128 v[192:195], v169 offset:2064
	v_mfma_f32_16x16x32_f16 v[8:11], v[136:139], v[184:187], v[8:11]
	ds_read_b128 v[196:199], v169 offset:3088
	v_mfma_f32_16x16x32_f16 v[12:15], v[140:143], v[184:187], v[12:15]
	v_mfma_f32_16x16x32_f16 v[16:19], v[144:147], v[184:187], v[16:19]
	v_mfma_f32_16x16x32_f16 v[20:23], v[132:135], v[188:191], v[20:23]
	v_mfma_f32_16x16x32_f16 v[24:27], v[136:139], v[188:191], v[24:27]
	v_mfma_f32_16x16x32_f16 v[28:31], v[140:143], v[188:191], v[28:31]
	v_mfma_f32_16x16x32_f16 v[32:35], v[144:147], v[188:191], v[32:35]
	s_waitcnt vmcnt(0) lgkmcnt(0)
	s_barrier
	s_add_i32 s52, s34, 0x6000
	s_cmp_lg_u32 s34, 0x12000
	s_cselect_b32 s52, s52, 0
	v_add_u32_e32 v168, s52, v165
	v_add_u32_e32 v169, s52, v164
	v_mfma_f32_16x16x32_f16 v[36:39], v[132:135], v[192:195], v[36:39]
	ds_read_b128 v[148:151], v168 offset:16
	ds_read_b128 v[184:187], v169 offset:16
	v_mfma_f32_16x16x32_f16 v[40:43], v[136:139], v[192:195], v[40:43]
	ds_read_b128 v[152:155], v168 offset:1040
	ds_read_b128 v[188:191], v169 offset:1040
	v_mfma_f32_16x16x32_f16 v[44:47], v[140:143], v[192:195], v[44:47]
	ds_read_b128 v[156:159], v168 offset:2064
	v_mfma_f32_16x16x32_f16 v[48:51], v[144:147], v[192:195], v[48:51]
	ds_read_b128 v[160:163], v168 offset:3088
	v_mfma_f32_16x16x32_f16 v[52:55], v[132:135], v[196:199], v[52:55]
	v_mfma_f32_16x16x32_f16 v[56:59], v[136:139], v[196:199], v[56:59]
	v_mfma_f32_16x16x32_f16 v[60:63], v[140:143], v[196:199], v[60:63]
	v_mfma_f32_16x16x32_f16 v[64:67], v[144:147], v[196:199], v[64:67]
	s_waitcnt lgkmcnt(0)
	s_mov_b32 s34, s52
	v_add_u32_e32 v169, s34, v164
	v_mfma_f32_16x16x32_f16 v[4:7], v[148:151], v[184:187], v[4:7]
	ds_read_b128 v[192:195], v169 offset:2064
	v_mfma_f32_16x16x32_f16 v[8:11], v[152:155], v[184:187], v[8:11]
	ds_read_b128 v[196:199], v169 offset:3088
	v_mfma_f32_16x16x32_f16 v[12:15], v[156:159], v[184:187], v[12:15]
	v_mfma_f32_16x16x32_f16 v[16:19], v[160:163], v[184:187], v[16:19]
	v_mfma_f32_16x16x32_f16 v[20:23], v[148:151], v[188:191], v[20:23]
	v_mfma_f32_16x16x32_f16 v[24:27], v[152:155], v[188:191], v[24:27]
	v_mfma_f32_16x16x32_f16 v[28:31], v[156:159], v[188:191], v[28:31]
	v_mfma_f32_16x16x32_f16 v[32:35], v[160:163], v[188:191], v[32:35]
	s_waitcnt lgkmcnt(0)
	s_barrier
	v_mfma_f32_16x16x32_f16 v[36:39], v[148:151], v[192:195], v[36:39]
	v_mfma_f32_16x16x32_f16 v[40:43], v[152:155], v[192:195], v[40:43]
	v_mfma_f32_16x16x32_f16 v[44:47], v[156:159], v[192:195], v[44:47]
	v_mfma_f32_16x16x32_f16 v[48:51], v[160:163], v[192:195], v[48:51]
	v_mfma_f32_16x16x32_f16 v[52:55], v[148:151], v[196:199], v[52:55]
	v_mfma_f32_16x16x32_f16 v[56:59], v[152:155], v[196:199], v[56:59]
	v_mfma_f32_16x16x32_f16 v[60:63], v[156:159], v[196:199], v[60:63]
	v_mfma_f32_16x16x32_f16 v[64:67], v[160:163], v[196:199], v[64:67]
	s_sub_u32 s77, s35, 0x1000
	s_lshr_b32 s77, s77, 12
	s_add_u32 s77, s77, 1
	s_cmp_lt_u32 s35, 0x1000
	s_cselect_b32 s77, 0, s77
	s_mul_i32 s77, s77, 0x6000
	s_add_u32 s68, s44, s77
	s_addc_u32 s69, s45, 0
	s_add_u32 s68, s68, 0xfa10600
	s_addc_u32 s69, s69, 0
	s_lshl_b32 s82, s35, 11
	s_add_u32 s80, s46, s82
	s_addc_u32 s81, s47, 0
	s_lshl_b32 s82, s30, 1
	s_add_u32 s80, s80, s82
	s_addc_u32 s81, s81, 0
	v_and_b32_e32 v172, 15, v200
	v_bfe_u32 v173, v200, 4, 2
	v_bfe_u32 v174, v200, 6, 1
	v_bfe_u32 v175, v200, 7, 2
	v_lshlrev_b32_e32 v176, 6, v174
	v_lshl_or_b32 v176, v173, 2, v176
	v_lshl_or_b32 v175, v175, 6, v172
	v_lshlrev_b32_e32 v175, 11, v175
	v_lshl_add_u32 v177, v176, 1, v175
	v_add_u32_e32 v176, s30, v176
	v_lshlrev_b32_e32 v176, 2, v176
	global_load_dwordx4 v[132:135], v176, s[68:69]
	global_load_dwordx4 v[136:139], v176, s[68:69] offset:64
	global_load_dwordx4 v[140:143], v176, s[68:69] offset:128
	global_load_dwordx4 v[144:147], v176, s[68:69] offset:192
	v_and_b32_e32 v172, 1, v173
	v_mul_u32_u24_e32 v172, 24, v172
	v_add_u32_e32 v177, v177, v172
	v_mov_b32_e32 v178, v177
	global_load_dwordx4 v[184:187], v178, s[80:81]
	global_load_dwordx4 v[188:191], v178, s[80:81] offset:64
	v_add_u32_e32 v178, 0x8000, v178
	global_load_dwordx4 v[192:195], v178, s[80:81]
	global_load_dwordx4 v[196:199], v178, s[80:81] offset:64
	s_waitcnt vmcnt(3)
	v_permlane16_swap_b32_e32 v184, v186
	v_permlane16_swap_b32_e32 v185, v187
	v_cvt_f32_f16_e32 v164, v184
	v_cvt_f32_f16_sdwa v165, v184 dst_sel:DWORD dst_unused:UNUSED_PAD src0_sel:WORD_1
	v_cvt_f32_f16_e32 v166, v185
	v_cvt_f32_f16_sdwa v167, v185 dst_sel:DWORD dst_unused:UNUSED_PAD src0_sel:WORD_1
	v_pk_mul_f32 v[164:165], v[164:165], s[84:85] op_sel_hi:[1,0]
	v_pk_mul_f32 v[166:167], v[166:167], s[84:85] op_sel_hi:[1,0]
	v_pk_fma_f32 v[4:5], v[4:5], v[132:133], v[164:165]
	v_pk_fma_f32 v[6:7], v[6:7], v[134:135], v[166:167]
	v_cvt_pk_f16_f32 v172, v4, v5
	v_cvt_pk_f16_f32 v173, v6, v7
	v_cvt_f32_f16_e32 v164, v186
	v_cvt_f32_f16_sdwa v165, v186 dst_sel:DWORD dst_unused:UNUSED_PAD src0_sel:WORD_1
	v_cvt_f32_f16_e32 v166, v187
	v_cvt_f32_f16_sdwa v167, v187 dst_sel:DWORD dst_unused:UNUSED_PAD src0_sel:WORD_1
	v_pk_mul_f32 v[164:165], v[164:165], s[84:85] op_sel_hi:[1,0]
	v_pk_mul_f32 v[166:167], v[166:167], s[84:85] op_sel_hi:[1,0]
	v_pk_fma_f32 v[8:9], v[8:9], v[136:137], v[164:165]
	v_pk_fma_f32 v[10:11], v[10:11], v[138:139], v[166:167]
	v_cvt_pk_f16_f32 v174, v8, v9
	v_cvt_pk_f16_f32 v175, v10, v11
	s_nop 1
	v_permlane16_swap_b32_e32 v172, v174
	v_permlane16_swap_b32_e32 v173, v175
	global_store_dwordx4 v177, v[172:175], s[80:81]
	s_waitcnt vmcnt(3)
	v_permlane16_swap_b32_e32 v188, v190
	v_permlane16_swap_b32_e32 v189, v191
	v_cvt_f32_f16_e32 v164, v188
	v_cvt_f32_f16_sdwa v165, v188 dst_sel:DWORD dst_unused:UNUSED_PAD src0_sel:WORD_1
	v_cvt_f32_f16_e32 v166, v189
	v_cvt_f32_f16_sdwa v167, v189 dst_sel:DWORD dst_unused:UNUSED_PAD src0_sel:WORD_1
	v_pk_mul_f32 v[164:165], v[164:165], s[84:85] op_sel_hi:[1,0]
	v_pk_mul_f32 v[166:167], v[166:167], s[84:85] op_sel_hi:[1,0]
	v_pk_fma_f32 v[12:13], v[12:13], v[140:141], v[164:165]
	v_pk_fma_f32 v[14:15], v[14:15], v[142:143], v[166:167]
	v_cvt_pk_f16_f32 v228, v12, v13
	v_cvt_pk_f16_f32 v229, v14, v15
	v_cvt_f32_f16_e32 v164, v190
	v_cvt_f32_f16_sdwa v165, v190 dst_sel:DWORD dst_unused:UNUSED_PAD src0_sel:WORD_1
	v_cvt_f32_f16_e32 v166, v191
	v_cvt_f32_f16_sdwa v167, v191 dst_sel:DWORD dst_unused:UNUSED_PAD src0_sel:WORD_1
	v_pk_mul_f32 v[164:165], v[164:165], s[84:85] op_sel_hi:[1,0]
	v_pk_mul_f32 v[166:167], v[166:167], s[84:85] op_sel_hi:[1,0]
	v_pk_fma_f32 v[16:17], v[16:17], v[144:145], v[164:165]
	v_pk_fma_f32 v[18:19], v[18:19], v[146:147], v[166:167]
	v_cvt_pk_f16_f32 v230, v16, v17
	v_cvt_pk_f16_f32 v231, v18, v19
	s_nop 1
	v_permlane16_swap_b32_e32 v228, v230
	v_permlane16_swap_b32_e32 v229, v231
	global_store_dwordx4 v177, v[228:231], s[80:81] offset:64
	v_add_u32_e32 v177, 0x8000, v177
	v_add_u32_e32 v178, 0x8000, v178
	global_load_dwordx4 v[184:187], v178, s[80:81]
	global_load_dwordx4 v[188:191], v178, s[80:81] offset:64
	s_waitcnt vmcnt(5)
	v_permlane16_swap_b32_e32 v192, v194
	v_permlane16_swap_b32_e32 v193, v195
	v_cvt_f32_f16_e32 v164, v192
	v_cvt_f32_f16_sdwa v165, v192 dst_sel:DWORD dst_unused:UNUSED_PAD src0_sel:WORD_1
	v_cvt_f32_f16_e32 v166, v193
	v_cvt_f32_f16_sdwa v167, v193 dst_sel:DWORD dst_unused:UNUSED_PAD src0_sel:WORD_1
	v_pk_mul_f32 v[164:165], v[164:165], s[84:85] op_sel_hi:[1,0]
	v_pk_mul_f32 v[166:167], v[166:167], s[84:85] op_sel_hi:[1,0]
	v_pk_fma_f32 v[20:21], v[20:21], v[132:133], v[164:165]
	v_pk_fma_f32 v[22:23], v[22:23], v[134:135], v[166:167]
	v_cvt_pk_f16_f32 v172, v20, v21
	v_cvt_pk_f16_f32 v173, v22, v23
	v_cvt_f32_f16_e32 v164, v194
	v_cvt_f32_f16_sdwa v165, v194 dst_sel:DWORD dst_unused:UNUSED_PAD src0_sel:WORD_1
	v_cvt_f32_f16_e32 v166, v195
	v_cvt_f32_f16_sdwa v167, v195 dst_sel:DWORD dst_unused:UNUSED_PAD src0_sel:WORD_1
	v_pk_mul_f32 v[164:165], v[164:165], s[84:85] op_sel_hi:[1,0]
	v_pk_mul_f32 v[166:167], v[166:167], s[84:85] op_sel_hi:[1,0]
	v_pk_fma_f32 v[24:25], v[24:25], v[136:137], v[164:165]
	v_pk_fma_f32 v[26:27], v[26:27], v[138:139], v[166:167]
	v_cvt_pk_f16_f32 v174, v24, v25
	v_cvt_pk_f16_f32 v175, v26, v27
	s_nop 1
	v_permlane16_swap_b32_e32 v172, v174
	v_permlane16_swap_b32_e32 v173, v175
	global_store_dwordx4 v177, v[172:175], s[80:81]
	s_waitcnt vmcnt(5)
	v_permlane16_swap_b32_e32 v196, v198
	v_permlane16_swap_b32_e32 v197, v199
	v_cvt_f32_f16_e32 v164, v196
	v_cvt_f32_f16_sdwa v165, v196 dst_sel:DWORD dst_unused:UNUSED_PAD src0_sel:WORD_1
	v_cvt_f32_f16_e32 v166, v197
	v_cvt_f32_f16_sdwa v167, v197 dst_sel:DWORD dst_unused:UNUSED_PAD src0_sel:WORD_1
	v_pk_mul_f32 v[164:165], v[164:165], s[84:85] op_sel_hi:[1,0]
	v_pk_mul_f32 v[166:167], v[166:167], s[84:85] op_sel_hi:[1,0]
	v_pk_fma_f32 v[28:29], v[28:29], v[140:141], v[164:165]
	v_pk_fma_f32 v[30:31], v[30:31], v[142:143], v[166:167]
	v_cvt_pk_f16_f32 v228, v28, v29
	v_cvt_pk_f16_f32 v229, v30, v31
	v_cvt_f32_f16_e32 v164, v198
	v_cvt_f32_f16_sdwa v165, v198 dst_sel:DWORD dst_unused:UNUSED_PAD src0_sel:WORD_1
	v_cvt_f32_f16_e32 v166, v199
	v_cvt_f32_f16_sdwa v167, v199 dst_sel:DWORD dst_unused:UNUSED_PAD src0_sel:WORD_1
	v_pk_mul_f32 v[164:165], v[164:165], s[84:85] op_sel_hi:[1,0]
	v_pk_mul_f32 v[166:167], v[166:167], s[84:85] op_sel_hi:[1,0]
	v_pk_fma_f32 v[32:33], v[32:33], v[144:145], v[164:165]
	v_pk_fma_f32 v[34:35], v[34:35], v[146:147], v[166:167]
	v_cvt_pk_f16_f32 v230, v32, v33
	v_cvt_pk_f16_f32 v231, v34, v35
	s_nop 1
	v_permlane16_swap_b32_e32 v228, v230
	v_permlane16_swap_b32_e32 v229, v231
	global_store_dwordx4 v177, v[228:231], s[80:81] offset:64
	v_add_u32_e32 v177, 0x8000, v177
	v_add_u32_e32 v178, 0x8000, v178
	global_load_dwordx4 v[192:195], v178, s[80:81]
	global_load_dwordx4 v[196:199], v178, s[80:81] offset:64
	s_waitcnt vmcnt(5)
	v_permlane16_swap_b32_e32 v184, v186
	v_permlane16_swap_b32_e32 v185, v187
	v_cvt_f32_f16_e32 v164, v184
	v_cvt_f32_f16_sdwa v165, v184 dst_sel:DWORD dst_unused:UNUSED_PAD src0_sel:WORD_1
	v_cvt_f32_f16_e32 v166, v185
	v_cvt_f32_f16_sdwa v167, v185 dst_sel:DWORD dst_unused:UNUSED_PAD src0_sel:WORD_1
	v_pk_mul_f32 v[164:165], v[164:165], s[84:85] op_sel_hi:[1,0]
	v_pk_mul_f32 v[166:167], v[166:167], s[84:85] op_sel_hi:[1,0]
	v_pk_fma_f32 v[36:37], v[36:37], v[132:133], v[164:165]
	v_pk_fma_f32 v[38:39], v[38:39], v[134:135], v[166:167]
	v_cvt_pk_f16_f32 v172, v36, v37
	v_cvt_pk_f16_f32 v173, v38, v39
	v_cvt_f32_f16_e32 v164, v186
	v_cvt_f32_f16_sdwa v165, v186 dst_sel:DWORD dst_unused:UNUSED_PAD src0_sel:WORD_1
	v_cvt_f32_f16_e32 v166, v187
	v_cvt_f32_f16_sdwa v167, v187 dst_sel:DWORD dst_unused:UNUSED_PAD src0_sel:WORD_1
	v_pk_mul_f32 v[164:165], v[164:165], s[84:85] op_sel_hi:[1,0]
	v_pk_mul_f32 v[166:167], v[166:167], s[84:85] op_sel_hi:[1,0]
	v_pk_fma_f32 v[40:41], v[40:41], v[136:137], v[164:165]
	v_pk_fma_f32 v[42:43], v[42:43], v[138:139], v[166:167]
	v_cvt_pk_f16_f32 v174, v40, v41
	v_cvt_pk_f16_f32 v175, v42, v43
	s_nop 1
	v_permlane16_swap_b32_e32 v172, v174
	v_permlane16_swap_b32_e32 v173, v175
	global_store_dwordx4 v177, v[172:175], s[80:81]
	s_waitcnt vmcnt(5)
	v_permlane16_swap_b32_e32 v188, v190
	v_permlane16_swap_b32_e32 v189, v191
	v_cvt_f32_f16_e32 v164, v188
	v_cvt_f32_f16_sdwa v165, v188 dst_sel:DWORD dst_unused:UNUSED_PAD src0_sel:WORD_1
	v_cvt_f32_f16_e32 v166, v189
	v_cvt_f32_f16_sdwa v167, v189 dst_sel:DWORD dst_unused:UNUSED_PAD src0_sel:WORD_1
	v_pk_mul_f32 v[164:165], v[164:165], s[84:85] op_sel_hi:[1,0]
	v_pk_mul_f32 v[166:167], v[166:167], s[84:85] op_sel_hi:[1,0]
	v_pk_fma_f32 v[44:45], v[44:45], v[140:141], v[164:165]
	v_pk_fma_f32 v[46:47], v[46:47], v[142:143], v[166:167]
	v_cvt_pk_f16_f32 v228, v44, v45
	v_cvt_pk_f16_f32 v229, v46, v47
	v_cvt_f32_f16_e32 v164, v190
	v_cvt_f32_f16_sdwa v165, v190 dst_sel:DWORD dst_unused:UNUSED_PAD src0_sel:WORD_1
	v_cvt_f32_f16_e32 v166, v191
	v_cvt_f32_f16_sdwa v167, v191 dst_sel:DWORD dst_unused:UNUSED_PAD src0_sel:WORD_1
	v_pk_mul_f32 v[164:165], v[164:165], s[84:85] op_sel_hi:[1,0]
	v_pk_mul_f32 v[166:167], v[166:167], s[84:85] op_sel_hi:[1,0]
	v_pk_fma_f32 v[48:49], v[48:49], v[144:145], v[164:165]
	v_pk_fma_f32 v[50:51], v[50:51], v[146:147], v[166:167]
	v_cvt_pk_f16_f32 v230, v48, v49
	v_cvt_pk_f16_f32 v231, v50, v51
	s_nop 1
	v_permlane16_swap_b32_e32 v228, v230
	v_permlane16_swap_b32_e32 v229, v231
	global_store_dwordx4 v177, v[228:231], s[80:81] offset:64
	v_add_u32_e32 v177, 0x8000, v177
	s_waitcnt vmcnt(3)
	v_permlane16_swap_b32_e32 v192, v194
	v_permlane16_swap_b32_e32 v193, v195
	v_cvt_f32_f16_e32 v164, v192
	v_cvt_f32_f16_sdwa v165, v192 dst_sel:DWORD dst_unused:UNUSED_PAD src0_sel:WORD_1
	v_cvt_f32_f16_e32 v166, v193
	v_cvt_f32_f16_sdwa v167, v193 dst_sel:DWORD dst_unused:UNUSED_PAD src0_sel:WORD_1
	v_pk_mul_f32 v[164:165], v[164:165], s[84:85] op_sel_hi:[1,0]
	v_pk_mul_f32 v[166:167], v[166:167], s[84:85] op_sel_hi:[1,0]
	v_pk_fma_f32 v[52:53], v[52:53], v[132:133], v[164:165]
	v_pk_fma_f32 v[54:55], v[54:55], v[134:135], v[166:167]
	v_cvt_pk_f16_f32 v172, v52, v53
	v_cvt_pk_f16_f32 v173, v54, v55
	v_cvt_f32_f16_e32 v164, v194
	v_cvt_f32_f16_sdwa v165, v194 dst_sel:DWORD dst_unused:UNUSED_PAD src0_sel:WORD_1
	v_cvt_f32_f16_e32 v166, v195
	v_cvt_f32_f16_sdwa v167, v195 dst_sel:DWORD dst_unused:UNUSED_PAD src0_sel:WORD_1
	v_pk_mul_f32 v[164:165], v[164:165], s[84:85] op_sel_hi:[1,0]
	v_pk_mul_f32 v[166:167], v[166:167], s[84:85] op_sel_hi:[1,0]
	v_pk_fma_f32 v[56:57], v[56:57], v[136:137], v[164:165]
	v_pk_fma_f32 v[58:59], v[58:59], v[138:139], v[166:167]
	v_cvt_pk_f16_f32 v174, v56, v57
	v_cvt_pk_f16_f32 v175, v58, v59
	s_nop 1
	v_permlane16_swap_b32_e32 v172, v174
	v_permlane16_swap_b32_e32 v173, v175
	global_store_dwordx4 v177, v[172:175], s[80:81]
	s_waitcnt vmcnt(3)
	v_permlane16_swap_b32_e32 v196, v198
	v_permlane16_swap_b32_e32 v197, v199
	v_cvt_f32_f16_e32 v164, v196
	v_cvt_f32_f16_sdwa v165, v196 dst_sel:DWORD dst_unused:UNUSED_PAD src0_sel:WORD_1
	v_cvt_f32_f16_e32 v166, v197
	v_cvt_f32_f16_sdwa v167, v197 dst_sel:DWORD dst_unused:UNUSED_PAD src0_sel:WORD_1
	v_pk_mul_f32 v[164:165], v[164:165], s[84:85] op_sel_hi:[1,0]
	v_pk_mul_f32 v[166:167], v[166:167], s[84:85] op_sel_hi:[1,0]
	v_pk_fma_f32 v[60:61], v[60:61], v[140:141], v[164:165]
	v_pk_fma_f32 v[62:63], v[62:63], v[142:143], v[166:167]
	v_cvt_pk_f16_f32 v228, v60, v61
	v_cvt_pk_f16_f32 v229, v62, v63
	v_cvt_f32_f16_e32 v164, v198
	v_cvt_f32_f16_sdwa v165, v198 dst_sel:DWORD dst_unused:UNUSED_PAD src0_sel:WORD_1
	v_cvt_f32_f16_e32 v166, v199
	v_cvt_f32_f16_sdwa v167, v199 dst_sel:DWORD dst_unused:UNUSED_PAD src0_sel:WORD_1
	v_pk_mul_f32 v[164:165], v[164:165], s[84:85] op_sel_hi:[1,0]
	v_pk_mul_f32 v[166:167], v[166:167], s[84:85] op_sel_hi:[1,0]
	v_pk_fma_f32 v[64:65], v[64:65], v[144:145], v[164:165]
	v_pk_fma_f32 v[66:67], v[66:67], v[146:147], v[166:167]
	v_cvt_pk_f16_f32 v230, v64, v65
	v_cvt_pk_f16_f32 v231, v66, v67
	s_nop 1
	v_permlane16_swap_b32_e32 v228, v230
	v_permlane16_swap_b32_e32 v229, v231
	global_store_dwordx4 v177, v[228:231], s[80:81] offset:64
	s_nop 1
	s_addk_i32 s24, 0x1000
	s_add_i32 s28, s25, 32
	s_cmp_gt_u32 s25, 31
	s_mov_b32 s25, s28
	s_cbranch_scc1 .LBB0_814
	s_branch .LBB0_764
